# GEMM main loop: the four mid-segment s_setprio 0 / s_setprio 1 flip pairs (between the two 16-MFMA halves of each MFMA segment) deleted
# speedup vs baseline: 1.0012x; 1.0012x over previous
; #define PG8_STAGE(bufoff, gbase, voff) do { _Pragma("unroll") for (int _i = 0; _i < 2; ++_i) \
;         __builtin_amdgcn_global_load_lds((const unsigned*)((const char*)(gbase) + (voff)[_i]), (LAS unsigned*)(lds + (bufoff) + ldsw + _i * 8192), 16, 0, 0); } while (0)
; #define PG8_LDA(dst, b, h) do { _Pragma("unroll") for (int m = 0; m < 4; ++m) _Pragma("unroll") for (int k = 0; k < 2; ++k) dst[m][k] = *(const LAS bf16x8*)(lds + PG8_SA(b, h) + aoff + m * 2048 + k * 1024); } while (0)
; #define PG8_LDB(dst, b, h) do { _Pragma("unroll") for (int n = 0; n < 2; ++n) _Pragma("unroll") for (int k = 0; k < 2; ++k) dst[n][k] = *(const LAS bf16x8*)(lds + PG8_SB(b, h) + boff + n * 2048 + k * 1024); } while (0)
; #define PG8_MMA(ai, bj, At, Bt) do { __builtin_amdgcn_s_setprio(1); _Pragma("unroll") for (int m = 0; m < 4; ++m) _Pragma("unroll") for (int n = 0; n < 2; ++n) _Pragma("unroll") for (int k = 0; k < 2; ++k) \
;         acc[ai][bj][m][n] = __builtin_amdgcn_mfma_f32_16x16x32_bf16(Bt[n][k], At[m][k], acc[ai][bj][m][n], 0, 0, 0); __builtin_amdgcn_s_setprio(0); } while (0)
; #define PG8_WAIT_V(n) asm volatile("s_waitcnt vmcnt(" #n ")" ::: "memory")
; #define PG8_WAIT_L(n) asm volatile("s_waitcnt lgkmcnt(" #n ")" ::: "memory")
; #define PG8_BAR __builtin_amdgcn_s_barrier()
; #define PG8_SCHED __builtin_amdgcn_sched_barrier(0)
; template <class EpiT>
; __device__ __forceinline__ void gemm_phase(LAS unsigned char* lds, const Gemm g, const StaticOrder& S, const EpiT& E, int wv) {
;     ...
;             PG8_LDB(B0, 0, 0); PG8_LDB(B1, 0, 1); PG8_SCHED; PG8_LDA(At, 0, 0); PG8_STAGE(PG8_SA(1, 1), a1 + hA, voffA);
;             PG8_WAIT_V(8); PG8_WAIT_L(0); PG8_BAR; PG8_MMA(0, 0, At, B0); PG8_MMA(0, 1, At, B1); PG8_BAR; PG8_SCHED;
;             PG8_LDA(At, 0, 1); PG8_STAGE(PG8_SB(0, 0), b2, voffB); PG8_STAGE(PG8_SB(0, 1), b2 + hB, voffB); PG8_STAGE(PG8_SA(0, 0), a2, voffA);
;             PG8_WAIT_V(8); PG8_WAIT_L(0); PG8_BAR; PG8_MMA(1, 0, At, B0); PG8_MMA(1, 1, At, B1); PG8_BAR; PG8_SCHED;
.LBB0_271:
	s_add_i32 s42, s22, 2
	s_add_u32 s43, s0, 0x80
	s_addc_u32 s23, s1, 0
	s_add_i32 s64, 0, 0x10000
	s_cmp_eq_u32 s52, s22
	s_cselect_b32 s23, s19, s23
	s_cselect_b32 s22, s18, s43
	v_add_u32_e32 v0, s64, v234
	s_cselect_b32 s45, s21, s41
	s_cselect_b32 s44, s20, s40
	s_add_i32 s43, 0, 0x14000
	ds_read_b128 v[134:137], v0
	ds_read_b128 v[138:141], v0 offset:1024
	ds_read_b128 v[142:145], v0 offset:2048
	ds_read_b128 v[146:149], v0 offset:3072
	v_add_u32_e32 v0, s43, v234
	ds_read_b128 v[150:153], v0
	ds_read_b128 v[154:157], v0 offset:1024
	ds_read_b128 v[158:161], v0 offset:2048
	ds_read_b128 v[162:165], v0 offset:3072
	s_add_i32 m0, s14, 0xc000
	ds_read_b128 v[166:169], v242
	ds_read_b128 v[170:173], v242 offset:1024
	ds_read_b128 v[174:177], v242 offset:2048
	ds_read_b128 v[178:181], v242 offset:3072
	ds_read_b128 v[204:207], v242 offset:4096
	ds_read_b128 v[208:211], v242 offset:5120
	ds_read_b128 v[212:215], v242 offset:6144
	ds_read_b128 v[216:219], v242 offset:7168
	global_load_lds_dwordx4 v196, s[0:1]
	s_add_i32 m0, s14, 0xe000
	s_nop 0
	global_load_lds_dwordx4 v198, s[0:1]
	s_waitcnt vmcnt(8)
	s_waitcnt lgkmcnt(0)
	s_barrier
	s_setprio 1
	s_waitcnt lgkmcnt(0)
	v_mfma_f32_16x16x32_bf16 v[130:133], v[134:137], v[166:169], v[130:133]
	v_mfma_f32_16x16x32_bf16 v[126:129], v[142:145], v[166:169], v[126:129]
	v_mfma_f32_16x16x32_bf16 v[114:117], v[134:137], v[174:177], v[114:117]
	v_mfma_f32_16x16x32_bf16 v[110:113], v[142:145], v[174:177], v[110:113]
	v_mfma_f32_16x16x32_bf16 v[98:101], v[134:137], v[204:207], v[98:101]
	v_mfma_f32_16x16x32_bf16 v[94:97], v[142:145], v[204:207], v[94:97]
	v_mfma_f32_16x16x32_bf16 v[82:85], v[134:137], v[212:215], v[82:85]
	v_mfma_f32_16x16x32_bf16 v[78:81], v[142:145], v[212:215], v[78:81]
	v_mfma_f32_16x16x32_bf16 v[130:133], v[138:141], v[170:173], v[130:133]
	v_mfma_f32_16x16x32_bf16 v[126:129], v[146:149], v[170:173], v[126:129]
	v_mfma_f32_16x16x32_bf16 v[114:117], v[138:141], v[178:181], v[114:117]
	v_mfma_f32_16x16x32_bf16 v[110:113], v[146:149], v[178:181], v[110:113]
	v_mfma_f32_16x16x32_bf16 v[98:101], v[138:141], v[208:211], v[98:101]
	v_mfma_f32_16x16x32_bf16 v[94:97], v[146:149], v[208:211], v[94:97]
	v_mfma_f32_16x16x32_bf16 v[82:85], v[138:141], v[216:219], v[82:85]
	v_mfma_f32_16x16x32_bf16 v[78:81], v[146:149], v[216:219], v[78:81]
	v_mfma_f32_16x16x32_bf16 v[122:125], v[150:153], v[166:169], v[122:125]
	v_mfma_f32_16x16x32_bf16 v[118:121], v[158:161], v[166:169], v[118:121]
	v_mfma_f32_16x16x32_bf16 v[106:109], v[150:153], v[174:177], v[106:109]
	v_mfma_f32_16x16x32_bf16 v[102:105], v[158:161], v[174:177], v[102:105]
	v_mfma_f32_16x16x32_bf16 v[90:93], v[150:153], v[204:207], v[90:93]
	v_mfma_f32_16x16x32_bf16 v[86:89], v[158:161], v[204:207], v[86:89]
	v_mfma_f32_16x16x32_bf16 v[74:77], v[150:153], v[212:215], v[74:77]
	v_mfma_f32_16x16x32_bf16 v[70:73], v[158:161], v[212:215], v[70:73]
	v_mfma_f32_16x16x32_bf16 v[122:125], v[154:157], v[170:173], v[122:125]
	v_mfma_f32_16x16x32_bf16 v[118:121], v[162:165], v[170:173], v[118:121]
	v_mfma_f32_16x16x32_bf16 v[106:109], v[154:157], v[178:181], v[106:109]
	v_mfma_f32_16x16x32_bf16 v[102:105], v[162:165], v[178:181], v[102:105]
	v_mfma_f32_16x16x32_bf16 v[90:93], v[154:157], v[208:211], v[90:93]
	v_mfma_f32_16x16x32_bf16 v[86:89], v[162:165], v[208:211], v[86:89]
	v_mfma_f32_16x16x32_bf16 v[74:77], v[154:157], v[216:219], v[74:77]
	v_mfma_f32_16x16x32_bf16 v[70:73], v[162:165], v[216:219], v[70:73]
	s_setprio 0
	s_barrier
	s_add_i32 s64, s64, s13
	s_mov_b32 m0, s64
	s_add_u32 s36, s44, 0x80
	s_addc_u32 s37, s45, 0
	ds_read_b128 v[166:169], v242 offset:16384
	ds_read_b128 v[170:173], v242 offset:17408
	ds_read_b128 v[174:177], v242 offset:18432
	ds_read_b128 v[178:181], v242 offset:19456
	ds_read_b128 v[204:207], v242 offset:20480
	ds_read_b128 v[208:211], v242 offset:21504
	ds_read_b128 v[212:215], v242 offset:22528
	ds_read_b128 v[216:219], v242 offset:23552
	global_load_lds_dwordx4 v182, s[44:45]
	s_add_i32 m0, s64, 0x2000
	s_add_i32 s43, s43, s13
	global_load_lds_dwordx4 v186, s[44:45]
	s_add_u32 s44, s44, s8
	s_addc_u32 s45, s45, 0
	s_mov_b32 m0, s43
	s_add_u32 s38, s44, 0x80
	s_addc_u32 s39, s45, 0
	global_load_lds_dwordx4 v182, s[44:45]
	s_add_i32 m0, s43, 0x2000
	s_add_u32 s46, s22, 0x80
	s_addc_u32 s47, s23, 0
	global_load_lds_dwordx4 v186, s[44:45]
	s_mov_b32 m0, s14
	s_nop 0
	global_load_lds_dwordx4 v14, s[22:23]
	s_mov_b32 m0, s15
	s_nop 0
	global_load_lds_dwordx4 v184, s[22:23]
	s_waitcnt vmcnt(8)
	s_waitcnt lgkmcnt(0)
	s_barrier
; #define PG8_STAGE(bufoff, gbase, voff) do { _Pragma("unroll") for (int _i = 0; _i < 2; ++_i) \
;         __builtin_amdgcn_global_load_lds((const unsigned*)((const char*)(gbase) + (voff)[_i]), (LAS unsigned*)(lds + (bufoff) + ldsw + _i * 8192), 16, 0, 0); } while (0)
; #define PG8_LDA(dst, b, h) do { _Pragma("unroll") for (int m = 0; m < 4; ++m) _Pragma("unroll") for (int k = 0; k < 2; ++k) dst[m][k] = *(const LAS bf16x8*)(lds + PG8_SA(b, h) + aoff + m * 2048 + k * 1024); } while (0)
; #define PG8_LDB(dst, b, h) do { _Pragma("unroll") for (int n = 0; n < 2; ++n) _Pragma("unroll") for (int k = 0; k < 2; ++k) dst[n][k] = *(const LAS bf16x8*)(lds + PG8_SB(b, h) + boff + n * 2048 + k * 1024); } while (0)
; #define PG8_MMA(ai, bj, At, Bt) do { __builtin_amdgcn_s_setprio(1); _Pragma("unroll") for (int m = 0; m < 4; ++m) _Pragma("unroll") for (int n = 0; n < 2; ++n) _Pragma("unroll") for (int k = 0; k < 2; ++k) \
;         acc[ai][bj][m][n] = __builtin_amdgcn_mfma_f32_16x16x32_bf16(Bt[n][k], At[m][k], acc[ai][bj][m][n], 0, 0, 0); __builtin_amdgcn_s_setprio(0); } while (0)
; #define PG8_WAIT_V(n) asm volatile("s_waitcnt vmcnt(" #n ")" ::: "memory")
; #define PG8_WAIT_L(n) asm volatile("s_waitcnt lgkmcnt(" #n ")" ::: "memory")
; #define PG8_BAR __builtin_amdgcn_s_barrier()
; #define PG8_SCHED __builtin_amdgcn_sched_barrier(0)
; template <class EpiT>
; __device__ __forceinline__ void gemm_phase(LAS unsigned char* lds, const Gemm g, const StaticOrder& S, const EpiT& E, int wv) {
;     ...
;             PG8_WAIT_V(8); PG8_WAIT_L(0); PG8_BAR; PG8_MMA(1, 0, At, B0); PG8_MMA(1, 1, At, B1); PG8_BAR; PG8_SCHED;
;             PG8_LDB(B0, 1, 0); PG8_LDB(B1, 1, 1); PG8_SCHED; PG8_LDA(At, 1, 0); PG8_STAGE(PG8_SA(0, 1), a2 + hA, voffA);
;             PG8_WAIT_V(8); PG8_WAIT_L(0); PG8_BAR; PG8_MMA(0, 0, At, B0); PG8_MMA(0, 1, At, B1); PG8_BAR; PG8_SCHED;
	s_setprio 1
	s_waitcnt lgkmcnt(0)
	v_mfma_f32_16x16x32_bf16 v[66:69], v[134:137], v[166:169], v[66:69]
	v_mfma_f32_16x16x32_bf16 v[62:65], v[142:145], v[166:169], v[62:65]
	v_mfma_f32_16x16x32_bf16 v[50:53], v[134:137], v[174:177], v[50:53]
	v_mfma_f32_16x16x32_bf16 v[46:49], v[142:145], v[174:177], v[46:49]
	v_mfma_f32_16x16x32_bf16 v[34:37], v[134:137], v[204:207], v[34:37]
	v_mfma_f32_16x16x32_bf16 v[30:33], v[142:145], v[204:207], v[30:33]
	v_mfma_f32_16x16x32_bf16 v[18:21], v[134:137], v[212:215], v[18:21]
	v_mfma_f32_16x16x32_bf16 v[10:13], v[142:145], v[212:215], v[10:13]
	v_mfma_f32_16x16x32_bf16 v[66:69], v[138:141], v[170:173], v[66:69]
	v_mfma_f32_16x16x32_bf16 v[62:65], v[146:149], v[170:173], v[62:65]
	v_mfma_f32_16x16x32_bf16 v[50:53], v[138:141], v[178:181], v[50:53]
	v_mfma_f32_16x16x32_bf16 v[46:49], v[146:149], v[178:181], v[46:49]
	v_mfma_f32_16x16x32_bf16 v[34:37], v[138:141], v[208:211], v[34:37]
	v_mfma_f32_16x16x32_bf16 v[30:33], v[146:149], v[208:211], v[30:33]
	v_mfma_f32_16x16x32_bf16 v[18:21], v[138:141], v[216:219], v[18:21]
	v_mfma_f32_16x16x32_bf16 v[10:13], v[146:149], v[216:219], v[10:13]
	v_mfma_f32_16x16x32_bf16 v[58:61], v[150:153], v[166:169], v[58:61]
	v_mfma_f32_16x16x32_bf16 v[54:57], v[158:161], v[166:169], v[54:57]
	v_mfma_f32_16x16x32_bf16 v[42:45], v[150:153], v[174:177], v[42:45]
	v_mfma_f32_16x16x32_bf16 v[38:41], v[158:161], v[174:177], v[38:41]
	v_mfma_f32_16x16x32_bf16 v[26:29], v[150:153], v[204:207], v[26:29]
	v_mfma_f32_16x16x32_bf16 v[22:25], v[158:161], v[204:207], v[22:25]
	v_mfma_f32_16x16x32_bf16 v[6:9], v[150:153], v[212:215], v[6:9]
	v_mfma_f32_16x16x32_bf16 v[2:5], v[158:161], v[212:215], v[2:5]
	v_mfma_f32_16x16x32_bf16 v[58:61], v[154:157], v[170:173], v[58:61]
	v_mfma_f32_16x16x32_bf16 v[54:57], v[162:165], v[170:173], v[54:57]
	v_mfma_f32_16x16x32_bf16 v[42:45], v[154:157], v[178:181], v[42:45]
	v_mfma_f32_16x16x32_bf16 v[38:41], v[162:165], v[178:181], v[38:41]
	v_mfma_f32_16x16x32_bf16 v[26:29], v[154:157], v[208:211], v[26:29]
	v_mfma_f32_16x16x32_bf16 v[22:25], v[162:165], v[208:211], v[22:25]
	v_mfma_f32_16x16x32_bf16 v[6:9], v[154:157], v[216:219], v[6:9]
	v_mfma_f32_16x16x32_bf16 v[2:5], v[162:165], v[216:219], v[2:5]
	s_setprio 0
	s_barrier
	s_add_i32 s43, 0, 0x18000
	v_add_u32_e32 v0, s43, v234
	s_add_i32 s44, 0, 0x1c000
	ds_read_b128 v[134:137], v0
	ds_read_b128 v[138:141], v0 offset:1024
	ds_read_b128 v[142:145], v0 offset:2048
	ds_read_b128 v[146:149], v0 offset:3072
	v_add_u32_e32 v0, s44, v234
	ds_read_b128 v[150:153], v0
	ds_read_b128 v[154:157], v0 offset:1024
	ds_read_b128 v[158:161], v0 offset:2048
	ds_read_b128 v[162:165], v0 offset:3072
	s_add_u32 s22, s22, s4
	s_addc_u32 s23, s23, 0
	s_mov_b32 m0, s88
	ds_read_b128 v[166:169], v242 offset:32768
	ds_read_b128 v[170:173], v242 offset:33792
	ds_read_b128 v[174:177], v242 offset:34816
	ds_read_b128 v[178:181], v242 offset:35840
	ds_read_b128 v[204:207], v242 offset:36864
	ds_read_b128 v[208:211], v242 offset:37888
	ds_read_b128 v[212:215], v242 offset:38912
	ds_read_b128 v[216:219], v242 offset:39936
	global_load_lds_dwordx4 v14, s[22:23]
	s_mov_b32 m0, s89
	s_nop 0
	global_load_lds_dwordx4 v184, s[22:23]
	s_waitcnt vmcnt(8)
	s_waitcnt lgkmcnt(0)
	s_barrier
	s_setprio 1
	s_waitcnt lgkmcnt(0)
	v_mfma_f32_16x16x32_bf16 v[130:133], v[134:137], v[166:169], v[130:133]
	v_mfma_f32_16x16x32_bf16 v[126:129], v[142:145], v[166:169], v[126:129]
	v_mfma_f32_16x16x32_bf16 v[114:117], v[134:137], v[174:177], v[114:117]
	v_mfma_f32_16x16x32_bf16 v[110:113], v[142:145], v[174:177], v[110:113]
	v_mfma_f32_16x16x32_bf16 v[98:101], v[134:137], v[204:207], v[98:101]
	v_mfma_f32_16x16x32_bf16 v[94:97], v[142:145], v[204:207], v[94:97]
	v_mfma_f32_16x16x32_bf16 v[82:85], v[134:137], v[212:215], v[82:85]
	v_mfma_f32_16x16x32_bf16 v[78:81], v[142:145], v[212:215], v[78:81]
	v_mfma_f32_16x16x32_bf16 v[130:133], v[138:141], v[170:173], v[130:133]
	v_mfma_f32_16x16x32_bf16 v[126:129], v[146:149], v[170:173], v[126:129]
	v_mfma_f32_16x16x32_bf16 v[114:117], v[138:141], v[178:181], v[114:117]
	v_mfma_f32_16x16x32_bf16 v[110:113], v[146:149], v[178:181], v[110:113]
	v_mfma_f32_16x16x32_bf16 v[98:101], v[138:141], v[208:211], v[98:101]
	v_mfma_f32_16x16x32_bf16 v[94:97], v[146:149], v[208:211], v[94:97]
	v_mfma_f32_16x16x32_bf16 v[82:85], v[138:141], v[216:219], v[82:85]
	v_mfma_f32_16x16x32_bf16 v[78:81], v[146:149], v[216:219], v[78:81]
	v_mfma_f32_16x16x32_bf16 v[122:125], v[150:153], v[166:169], v[122:125]
	v_mfma_f32_16x16x32_bf16 v[118:121], v[158:161], v[166:169], v[118:121]
	v_mfma_f32_16x16x32_bf16 v[106:109], v[150:153], v[174:177], v[106:109]
	v_mfma_f32_16x16x32_bf16 v[102:105], v[158:161], v[174:177], v[102:105]
	v_mfma_f32_16x16x32_bf16 v[90:93], v[150:153], v[204:207], v[90:93]
	v_mfma_f32_16x16x32_bf16 v[86:89], v[158:161], v[204:207], v[86:89]
	v_mfma_f32_16x16x32_bf16 v[74:77], v[150:153], v[212:215], v[74:77]
	v_mfma_f32_16x16x32_bf16 v[70:73], v[158:161], v[212:215], v[70:73]
	v_mfma_f32_16x16x32_bf16 v[122:125], v[154:157], v[170:173], v[122:125]
	v_mfma_f32_16x16x32_bf16 v[118:121], v[162:165], v[170:173], v[118:121]
	v_mfma_f32_16x16x32_bf16 v[106:109], v[154:157], v[178:181], v[106:109]
	v_mfma_f32_16x16x32_bf16 v[102:105], v[162:165], v[178:181], v[102:105]
	v_mfma_f32_16x16x32_bf16 v[90:93], v[154:157], v[208:211], v[90:93]
	v_mfma_f32_16x16x32_bf16 v[86:89], v[162:165], v[208:211], v[86:89]
	v_mfma_f32_16x16x32_bf16 v[74:77], v[154:157], v[216:219], v[74:77]
	v_mfma_f32_16x16x32_bf16 v[70:73], v[162:165], v[216:219], v[70:73]
	s_setprio 0
	s_barrier
; #define PG8_STAGE(bufoff, gbase, voff) do { _Pragma("unroll") for (int _i = 0; _i < 2; ++_i) \
;         __builtin_amdgcn_global_load_lds((const unsigned*)((const char*)(gbase) + (voff)[_i]), (LAS unsigned*)(lds + (bufoff) + ldsw + _i * 8192), 16, 0, 0); } while (0)
; #define PG8_LDA(dst, b, h) do { _Pragma("unroll") for (int m = 0; m < 4; ++m) _Pragma("unroll") for (int k = 0; k < 2; ++k) dst[m][k] = *(const LAS bf16x8*)(lds + PG8_SA(b, h) + aoff + m * 2048 + k * 1024); } while (0)
; #define PG8_MMA(ai, bj, At, Bt) do { __builtin_amdgcn_s_setprio(1); _Pragma("unroll") for (int m = 0; m < 4; ++m) _Pragma("unroll") for (int n = 0; n < 2; ++n) _Pragma("unroll") for (int k = 0; k < 2; ++k) \
;         acc[ai][bj][m][n] = __builtin_amdgcn_mfma_f32_16x16x32_bf16(Bt[n][k], At[m][k], acc[ai][bj][m][n], 0, 0, 0); __builtin_amdgcn_s_setprio(0); } while (0)
; #define PG8_WAIT_V(n) asm volatile("s_waitcnt vmcnt(" #n ")" ::: "memory")
; #define PG8_WAIT_L(n) asm volatile("s_waitcnt lgkmcnt(" #n ")" ::: "memory")
; #define PG8_BAR __builtin_amdgcn_s_barrier()
; #define PG8_SCHED __builtin_amdgcn_sched_barrier(0)
; template <class EpiT>
; __device__ __forceinline__ void gemm_phase(LAS unsigned char* lds, const Gemm g, const StaticOrder& S, const EpiT& E, int wv) {
;     ...
;             PG8_LDA(At, 1, 1); PG8_STAGE(PG8_SB(1, 0), b3, voffB); PG8_STAGE(PG8_SB(1, 1), b3 + hB, voffB); PG8_STAGE(PG8_SA(1, 0), a3, voffA);
;             PG8_WAIT_V(8); PG8_WAIT_L(0); PG8_BAR; PG8_MMA(1, 0, At, B0); PG8_MMA(1, 1, At, B1); PG8_BAR; PG8_SCHED;
;         }
	s_add_i32 s22, s43, s13
	s_mov_b32 m0, s22
	ds_read_b128 v[166:169], v242 offset:49152
	ds_read_b128 v[170:173], v242 offset:50176
	ds_read_b128 v[174:177], v242 offset:51200
	ds_read_b128 v[178:181], v242 offset:52224
	ds_read_b128 v[204:207], v242 offset:53248
	ds_read_b128 v[208:211], v242 offset:54272
	ds_read_b128 v[212:215], v242 offset:55296
	ds_read_b128 v[216:219], v242 offset:56320
	global_load_lds_dwordx4 v182, s[36:37]
	s_add_i32 m0, s22, 0x2000
	s_add_i32 s22, s44, s13
	global_load_lds_dwordx4 v186, s[36:37]
	s_mov_b32 m0, s22
	s_nop 0
	global_load_lds_dwordx4 v182, s[38:39]
	s_add_i32 m0, s22, 0x2000
	s_nop 0
	global_load_lds_dwordx4 v186, s[38:39]
	s_mov_b32 m0, s72
	s_nop 0
	global_load_lds_dwordx4 v14, s[46:47]
	s_mov_b32 m0, s73
	s_nop 0
	global_load_lds_dwordx4 v184, s[46:47]
	s_waitcnt vmcnt(8)
	s_waitcnt lgkmcnt(0)
	s_barrier
	s_setprio 1
	s_waitcnt lgkmcnt(0)
	v_mfma_f32_16x16x32_bf16 v[66:69], v[134:137], v[166:169], v[66:69]
	v_mfma_f32_16x16x32_bf16 v[62:65], v[142:145], v[166:169], v[62:65]
	v_mfma_f32_16x16x32_bf16 v[50:53], v[134:137], v[174:177], v[50:53]
	v_mfma_f32_16x16x32_bf16 v[46:49], v[142:145], v[174:177], v[46:49]
	v_mfma_f32_16x16x32_bf16 v[34:37], v[134:137], v[204:207], v[34:37]
	v_mfma_f32_16x16x32_bf16 v[30:33], v[142:145], v[204:207], v[30:33]
	v_mfma_f32_16x16x32_bf16 v[18:21], v[134:137], v[212:215], v[18:21]
	v_mfma_f32_16x16x32_bf16 v[10:13], v[142:145], v[212:215], v[10:13]
	v_mfma_f32_16x16x32_bf16 v[66:69], v[138:141], v[170:173], v[66:69]
	v_mfma_f32_16x16x32_bf16 v[62:65], v[146:149], v[170:173], v[62:65]
	v_mfma_f32_16x16x32_bf16 v[50:53], v[138:141], v[178:181], v[50:53]
	v_mfma_f32_16x16x32_bf16 v[46:49], v[146:149], v[178:181], v[46:49]
	v_mfma_f32_16x16x32_bf16 v[34:37], v[138:141], v[208:211], v[34:37]
	v_mfma_f32_16x16x32_bf16 v[30:33], v[146:149], v[208:211], v[30:33]
	v_mfma_f32_16x16x32_bf16 v[18:21], v[138:141], v[216:219], v[18:21]
	v_mfma_f32_16x16x32_bf16 v[10:13], v[146:149], v[216:219], v[10:13]
	v_mfma_f32_16x16x32_bf16 v[58:61], v[150:153], v[166:169], v[58:61]
	v_mfma_f32_16x16x32_bf16 v[54:57], v[158:161], v[166:169], v[54:57]
	v_mfma_f32_16x16x32_bf16 v[42:45], v[150:153], v[174:177], v[42:45]
	v_mfma_f32_16x16x32_bf16 v[38:41], v[158:161], v[174:177], v[38:41]
	v_mfma_f32_16x16x32_bf16 v[26:29], v[150:153], v[204:207], v[26:29]
	v_mfma_f32_16x16x32_bf16 v[22:25], v[158:161], v[204:207], v[22:25]
	v_mfma_f32_16x16x32_bf16 v[6:9], v[150:153], v[212:215], v[6:9]
	v_mfma_f32_16x16x32_bf16 v[2:5], v[158:161], v[212:215], v[2:5]
	v_mfma_f32_16x16x32_bf16 v[58:61], v[154:157], v[170:173], v[58:61]
	v_mfma_f32_16x16x32_bf16 v[54:57], v[162:165], v[170:173], v[54:57]
	v_mfma_f32_16x16x32_bf16 v[42:45], v[154:157], v[178:181], v[42:45]
	v_mfma_f32_16x16x32_bf16 v[38:41], v[162:165], v[178:181], v[38:41]
	v_mfma_f32_16x16x32_bf16 v[26:29], v[154:157], v[208:211], v[26:29]
	v_mfma_f32_16x16x32_bf16 v[22:25], v[162:165], v[208:211], v[22:25]
	v_mfma_f32_16x16x32_bf16 v[6:9], v[154:157], v[216:219], v[6:9]
	v_mfma_f32_16x16x32_bf16 v[2:5], v[162:165], v[216:219], v[2:5]
	s_setprio 0
	s_barrier
	s_add_u32 s0, s0, 0x100
	s_addc_u32 s1, s1, 0
	s_add_u32 s40, s40, 0x100
	s_addc_u32 s41, s41, 0
	s_cmp_ge_i32 s42, s81
	s_mov_b32 s22, s42
	s_cbranch_scc0 .LBB0_271
	s_and_b64 vcc, exec, s[16:17]
	s_cbranch_vccnz .LBB0_278
